# phase 0 silu(c) fill: 34 serialized load-wait-store iterations replaced by 34 loads in flight then the activations
# speedup vs baseline: 1.0128x; 1.0023x over previous
; DI float siluf_(float x) { return x * __builtin_amdgcn_rcpf(1.f + __expf(-x)); }
; DI void phase0(const Params& p, unsigned char* smem) {
;     ...
;         for (int idx = tid; idx < 17 * 1024; idx += 512) { const float v = idx < 16384 ? p.c[idx] : p.c_ctx[idx - 16384]; sc[idx] = siluf_(v); }
.LBB0_9:
	v_lshlrev_b32_e32 v4, 2, v180
	v_mov_b32_e32 v5, 0
	s_mov_b32 s4, 0xffff0000
	s_waitcnt lgkmcnt(0)
	v_lshl_add_u64 v[2:3], s[42:43], 0, v[4:5]
	s_mov_b32 s5, -1
	v_add_u32_e32 v6, 0, v4
	v_lshl_add_u64 v[2:3], v[2:3], 0, s[4:5]
	v_lshl_add_u64 v[4:5], s[38:39], 0, v[4:5]
	s_mov_b64 s[4:5], 0
	s_movk_i32 s3, 0x4000
	s_mov_b64 s[6:7], 0x800
	s_movk_i32 s8, 0x41ff
	v_mov_b32_e32 v7, v180
	v_lshlrev_b32_e32 v150, 2, v180
	v_lshlrev_b32_e32 v151, 2, v180
	global_load_dword v100, v150, s[38:39]
	v_add_u32_e32 v150, 0x800, v150
	global_load_dword v101, v150, s[38:39]
	v_add_u32_e32 v150, 0x800, v150
	global_load_dword v102, v150, s[38:39]
	v_add_u32_e32 v150, 0x800, v150
	global_load_dword v103, v150, s[38:39]
	v_add_u32_e32 v150, 0x800, v150
	global_load_dword v104, v150, s[38:39]
	v_add_u32_e32 v150, 0x800, v150
	global_load_dword v105, v150, s[38:39]
	v_add_u32_e32 v150, 0x800, v150
	global_load_dword v106, v150, s[38:39]
	v_add_u32_e32 v150, 0x800, v150
	global_load_dword v107, v150, s[38:39]
	v_add_u32_e32 v150, 0x800, v150
	global_load_dword v108, v150, s[38:39]
	v_add_u32_e32 v150, 0x800, v150
	global_load_dword v109, v150, s[38:39]
	v_add_u32_e32 v150, 0x800, v150
	global_load_dword v110, v150, s[38:39]
	v_add_u32_e32 v150, 0x800, v150
	global_load_dword v111, v150, s[38:39]
	v_add_u32_e32 v150, 0x800, v150
	global_load_dword v112, v150, s[38:39]
	v_add_u32_e32 v150, 0x800, v150
	global_load_dword v113, v150, s[38:39]
	v_add_u32_e32 v150, 0x800, v150
	global_load_dword v114, v150, s[38:39]
	v_add_u32_e32 v150, 0x800, v150
	global_load_dword v115, v150, s[38:39]
	v_add_u32_e32 v150, 0x800, v150
	global_load_dword v116, v150, s[38:39]
	v_add_u32_e32 v150, 0x800, v150
	global_load_dword v117, v150, s[38:39]
	v_add_u32_e32 v150, 0x800, v150
	global_load_dword v118, v150, s[38:39]
	v_add_u32_e32 v150, 0x800, v150
	global_load_dword v119, v150, s[38:39]
	v_add_u32_e32 v150, 0x800, v150
	global_load_dword v120, v150, s[38:39]
	v_add_u32_e32 v150, 0x800, v150
	global_load_dword v121, v150, s[38:39]
	v_add_u32_e32 v150, 0x800, v150
	global_load_dword v122, v150, s[38:39]
	v_add_u32_e32 v150, 0x800, v150
	global_load_dword v123, v150, s[38:39]
	v_add_u32_e32 v150, 0x800, v150
	global_load_dword v124, v150, s[38:39]
	v_add_u32_e32 v150, 0x800, v150
	global_load_dword v125, v150, s[38:39]
	v_add_u32_e32 v150, 0x800, v150
	global_load_dword v126, v150, s[38:39]
	v_add_u32_e32 v150, 0x800, v150
	global_load_dword v127, v150, s[38:39]
	v_add_u32_e32 v150, 0x800, v150
	global_load_dword v128, v150, s[38:39]
	v_add_u32_e32 v150, 0x800, v150
	global_load_dword v129, v150, s[38:39]
	v_add_u32_e32 v150, 0x800, v150
	global_load_dword v130, v150, s[38:39]
	v_add_u32_e32 v150, 0x800, v150
	global_load_dword v131, v150, s[38:39]
	v_add_u32_e32 v150, 0x800, v150
	global_load_dword v132, v151, s[42:43]
	v_add_u32_e32 v152, 0x800, v151
	global_load_dword v133, v152, s[42:43]
	v_add_u32_e32 v153, 0x10000, v151
	s_waitcnt vmcnt(33)
	v_mul_f32_e32 v154, 0xbfb8aa3b, v100
	v_exp_f32_e32 v154, v154
	s_nop 0
	v_add_f32_e32 v154, 1.0, v154
	v_rcp_f32_e32 v154, v154
	s_nop 0
	v_mul_f32_e32 v154, v100, v154
	ds_write_b32 v151, v154 offset:0
	s_waitcnt vmcnt(32)
	v_mul_f32_e32 v155, 0xbfb8aa3b, v101
	v_exp_f32_e32 v155, v155
	s_nop 0
	v_add_f32_e32 v155, 1.0, v155
	v_rcp_f32_e32 v155, v155
	s_nop 0
	v_mul_f32_e32 v155, v101, v155
	ds_write_b32 v151, v155 offset:2048
	s_waitcnt vmcnt(31)
	v_mul_f32_e32 v154, 0xbfb8aa3b, v102
	v_exp_f32_e32 v154, v154
	s_nop 0
	v_add_f32_e32 v154, 1.0, v154
	v_rcp_f32_e32 v154, v154
	s_nop 0
	v_mul_f32_e32 v154, v102, v154
	ds_write_b32 v151, v154 offset:4096
	s_waitcnt vmcnt(30)
	v_mul_f32_e32 v155, 0xbfb8aa3b, v103
	v_exp_f32_e32 v155, v155
	s_nop 0
	v_add_f32_e32 v155, 1.0, v155
	v_rcp_f32_e32 v155, v155
	s_nop 0
	v_mul_f32_e32 v155, v103, v155
	ds_write_b32 v151, v155 offset:6144
	s_waitcnt vmcnt(29)
	v_mul_f32_e32 v154, 0xbfb8aa3b, v104
	v_exp_f32_e32 v154, v154
	s_nop 0
	v_add_f32_e32 v154, 1.0, v154
	v_rcp_f32_e32 v154, v154
	s_nop 0
	v_mul_f32_e32 v154, v104, v154
	ds_write_b32 v151, v154 offset:8192
	s_waitcnt vmcnt(28)
	v_mul_f32_e32 v155, 0xbfb8aa3b, v105
	v_exp_f32_e32 v155, v155
	s_nop 0
	v_add_f32_e32 v155, 1.0, v155
	v_rcp_f32_e32 v155, v155
	s_nop 0
	v_mul_f32_e32 v155, v105, v155
	ds_write_b32 v151, v155 offset:10240
	s_waitcnt vmcnt(27)
	v_mul_f32_e32 v154, 0xbfb8aa3b, v106
	v_exp_f32_e32 v154, v154
	s_nop 0
	v_add_f32_e32 v154, 1.0, v154
	v_rcp_f32_e32 v154, v154
	s_nop 0
	v_mul_f32_e32 v154, v106, v154
	ds_write_b32 v151, v154 offset:12288
	s_waitcnt vmcnt(26)
	v_mul_f32_e32 v155, 0xbfb8aa3b, v107
	v_exp_f32_e32 v155, v155
	s_nop 0
	v_add_f32_e32 v155, 1.0, v155
	v_rcp_f32_e32 v155, v155
	s_nop 0
	v_mul_f32_e32 v155, v107, v155
	ds_write_b32 v151, v155 offset:14336
	s_waitcnt vmcnt(25)
	v_mul_f32_e32 v154, 0xbfb8aa3b, v108
	v_exp_f32_e32 v154, v154
	s_nop 0
	v_add_f32_e32 v154, 1.0, v154
	v_rcp_f32_e32 v154, v154
	s_nop 0
	v_mul_f32_e32 v154, v108, v154
	ds_write_b32 v151, v154 offset:16384
	s_waitcnt vmcnt(24)
	v_mul_f32_e32 v155, 0xbfb8aa3b, v109
	v_exp_f32_e32 v155, v155
	s_nop 0
	v_add_f32_e32 v155, 1.0, v155
	v_rcp_f32_e32 v155, v155
	s_nop 0
	v_mul_f32_e32 v155, v109, v155
	ds_write_b32 v151, v155 offset:18432
	s_waitcnt vmcnt(23)
	v_mul_f32_e32 v154, 0xbfb8aa3b, v110
	v_exp_f32_e32 v154, v154
	s_nop 0
	v_add_f32_e32 v154, 1.0, v154
	v_rcp_f32_e32 v154, v154
	s_nop 0
	v_mul_f32_e32 v154, v110, v154
	ds_write_b32 v151, v154 offset:20480
	s_waitcnt vmcnt(22)
	v_mul_f32_e32 v155, 0xbfb8aa3b, v111
	v_exp_f32_e32 v155, v155
	s_nop 0
	v_add_f32_e32 v155, 1.0, v155
	v_rcp_f32_e32 v155, v155
	s_nop 0
	v_mul_f32_e32 v155, v111, v155
	ds_write_b32 v151, v155 offset:22528
	s_waitcnt vmcnt(21)
; DI float siluf_(float x) { return x * __builtin_amdgcn_rcpf(1.f + __expf(-x)); }
; DI void phase0(const Params& p, unsigned char* smem) {
;     ...
;         for (int idx = tid; idx < 17 * 1024; idx += 512) { const float v = idx < 16384 ? p.c[idx] : p.c_ctx[idx - 16384]; sc[idx] = siluf_(v); }
;         __syncthreads();
;         for (int item = blockIdx.x; item < 192; item += gridDim.x) {
;             const int col = item * 32 + (lane & 31), kh = lane >> 5;
;             float acc[17];
; #pragma unroll
;             for (int b = 0; b < 17; ++b) acc[b] = 0.f;
; #pragma unroll 4
;             for (int kk = 0; kk < 64; ++kk) {
;                 const int k = 128 * wave + 2 * kk + kh; const float wv = p.w_mod[(size_t)k * NMODC + col];
	v_mul_f32_e32 v154, 0xbfb8aa3b, v112
	v_exp_f32_e32 v154, v154
	s_nop 0
	v_add_f32_e32 v154, 1.0, v154
	v_rcp_f32_e32 v154, v154
	s_nop 0
	v_mul_f32_e32 v154, v112, v154
	ds_write_b32 v151, v154 offset:24576
	s_waitcnt vmcnt(20)
	v_mul_f32_e32 v155, 0xbfb8aa3b, v113
	v_exp_f32_e32 v155, v155
	s_nop 0
	v_add_f32_e32 v155, 1.0, v155
	v_rcp_f32_e32 v155, v155
	s_nop 0
	v_mul_f32_e32 v155, v113, v155
	ds_write_b32 v151, v155 offset:26624
	s_waitcnt vmcnt(19)
	v_mul_f32_e32 v154, 0xbfb8aa3b, v114
	v_exp_f32_e32 v154, v154
	s_nop 0
	v_add_f32_e32 v154, 1.0, v154
	v_rcp_f32_e32 v154, v154
	s_nop 0
	v_mul_f32_e32 v154, v114, v154
	ds_write_b32 v151, v154 offset:28672
	s_waitcnt vmcnt(18)
	v_mul_f32_e32 v155, 0xbfb8aa3b, v115
	v_exp_f32_e32 v155, v155
	s_nop 0
	v_add_f32_e32 v155, 1.0, v155
	v_rcp_f32_e32 v155, v155
	s_nop 0
	v_mul_f32_e32 v155, v115, v155
	ds_write_b32 v151, v155 offset:30720
	s_waitcnt vmcnt(17)
	v_mul_f32_e32 v154, 0xbfb8aa3b, v116
	v_exp_f32_e32 v154, v154
	s_nop 0
	v_add_f32_e32 v154, 1.0, v154
	v_rcp_f32_e32 v154, v154
	s_nop 0
	v_mul_f32_e32 v154, v116, v154
	ds_write_b32 v151, v154 offset:32768
	s_waitcnt vmcnt(16)
	v_mul_f32_e32 v155, 0xbfb8aa3b, v117
	v_exp_f32_e32 v155, v155
	s_nop 0
	v_add_f32_e32 v155, 1.0, v155
	v_rcp_f32_e32 v155, v155
	s_nop 0
	v_mul_f32_e32 v155, v117, v155
	ds_write_b32 v151, v155 offset:34816
	s_waitcnt vmcnt(15)
	v_mul_f32_e32 v154, 0xbfb8aa3b, v118
	v_exp_f32_e32 v154, v154
	s_nop 0
	v_add_f32_e32 v154, 1.0, v154
	v_rcp_f32_e32 v154, v154
	s_nop 0
	v_mul_f32_e32 v154, v118, v154
	ds_write_b32 v151, v154 offset:36864
	s_waitcnt vmcnt(14)
	v_mul_f32_e32 v155, 0xbfb8aa3b, v119
	v_exp_f32_e32 v155, v155
	s_nop 0
	v_add_f32_e32 v155, 1.0, v155
	v_rcp_f32_e32 v155, v155
	s_nop 0
	v_mul_f32_e32 v155, v119, v155
	ds_write_b32 v151, v155 offset:38912
	s_waitcnt vmcnt(13)
	v_mul_f32_e32 v154, 0xbfb8aa3b, v120
	v_exp_f32_e32 v154, v154
	s_nop 0
	v_add_f32_e32 v154, 1.0, v154
	v_rcp_f32_e32 v154, v154
	s_nop 0
	v_mul_f32_e32 v154, v120, v154
	ds_write_b32 v151, v154 offset:40960
	s_waitcnt vmcnt(12)
	v_mul_f32_e32 v155, 0xbfb8aa3b, v121
	v_exp_f32_e32 v155, v155
	s_nop 0
	v_add_f32_e32 v155, 1.0, v155
	v_rcp_f32_e32 v155, v155
	s_nop 0
	v_mul_f32_e32 v155, v121, v155
	ds_write_b32 v151, v155 offset:43008
	s_waitcnt vmcnt(11)
	v_mul_f32_e32 v154, 0xbfb8aa3b, v122
	v_exp_f32_e32 v154, v154
	s_nop 0
	v_add_f32_e32 v154, 1.0, v154
	v_rcp_f32_e32 v154, v154
	s_nop 0
	v_mul_f32_e32 v154, v122, v154
	ds_write_b32 v151, v154 offset:45056
	s_waitcnt vmcnt(10)
	v_mul_f32_e32 v155, 0xbfb8aa3b, v123
	v_exp_f32_e32 v155, v155
	s_nop 0
	v_add_f32_e32 v155, 1.0, v155
	v_rcp_f32_e32 v155, v155
	s_nop 0
	v_mul_f32_e32 v155, v123, v155
	ds_write_b32 v151, v155 offset:47104
	s_waitcnt vmcnt(9)
	v_mul_f32_e32 v154, 0xbfb8aa3b, v124
	v_exp_f32_e32 v154, v154
	s_nop 0
	v_add_f32_e32 v154, 1.0, v154
	v_rcp_f32_e32 v154, v154
	s_nop 0
	v_mul_f32_e32 v154, v124, v154
	ds_write_b32 v151, v154 offset:49152
	s_waitcnt vmcnt(8)
	v_mul_f32_e32 v155, 0xbfb8aa3b, v125
	v_exp_f32_e32 v155, v155
	s_nop 0
	v_add_f32_e32 v155, 1.0, v155
	v_rcp_f32_e32 v155, v155
	s_nop 0
	v_mul_f32_e32 v155, v125, v155
	ds_write_b32 v151, v155 offset:51200
	s_waitcnt vmcnt(7)
	v_mul_f32_e32 v154, 0xbfb8aa3b, v126
	v_exp_f32_e32 v154, v154
	s_nop 0
	v_add_f32_e32 v154, 1.0, v154
	v_rcp_f32_e32 v154, v154
	s_nop 0
	v_mul_f32_e32 v154, v126, v154
	ds_write_b32 v151, v154 offset:53248
	s_waitcnt vmcnt(6)
	v_mul_f32_e32 v155, 0xbfb8aa3b, v127
	v_exp_f32_e32 v155, v155
	s_nop 0
	v_add_f32_e32 v155, 1.0, v155
	v_rcp_f32_e32 v155, v155
	s_nop 0
	v_mul_f32_e32 v155, v127, v155
	ds_write_b32 v151, v155 offset:55296
	s_waitcnt vmcnt(5)
	v_mul_f32_e32 v154, 0xbfb8aa3b, v128
	v_exp_f32_e32 v154, v154
	s_nop 0
	v_add_f32_e32 v154, 1.0, v154
	v_rcp_f32_e32 v154, v154
	s_nop 0
	v_mul_f32_e32 v154, v128, v154
	ds_write_b32 v151, v154 offset:57344
	s_waitcnt vmcnt(4)
	v_mul_f32_e32 v155, 0xbfb8aa3b, v129
	v_exp_f32_e32 v155, v155
	s_nop 0
	v_add_f32_e32 v155, 1.0, v155
	v_rcp_f32_e32 v155, v155
	s_nop 0
	v_mul_f32_e32 v155, v129, v155
	ds_write_b32 v151, v155 offset:59392
	s_waitcnt vmcnt(3)
	v_mul_f32_e32 v154, 0xbfb8aa3b, v130
	v_exp_f32_e32 v154, v154
	s_nop 0
	v_add_f32_e32 v154, 1.0, v154
	v_rcp_f32_e32 v154, v154
	s_nop 0
	v_mul_f32_e32 v154, v130, v154
	ds_write_b32 v151, v154 offset:61440
	s_waitcnt vmcnt(2)
	v_mul_f32_e32 v155, 0xbfb8aa3b, v131
	v_exp_f32_e32 v155, v155
	s_nop 0
	v_add_f32_e32 v155, 1.0, v155
	v_rcp_f32_e32 v155, v155
	s_nop 0
	v_mul_f32_e32 v155, v131, v155
	ds_write_b32 v151, v155 offset:63488
	s_waitcnt vmcnt(1)
	v_mul_f32_e32 v154, 0xbfb8aa3b, v132
	v_exp_f32_e32 v154, v154
	s_nop 0
	v_add_f32_e32 v154, 1.0, v154
	v_rcp_f32_e32 v154, v154
	s_nop 0
	v_mul_f32_e32 v154, v132, v154
	ds_write_b32 v153, v154 offset:0
	s_waitcnt vmcnt(0)
	v_mul_f32_e32 v155, 0xbfb8aa3b, v133
	v_exp_f32_e32 v155, v155
	s_nop 0
	v_add_f32_e32 v155, 1.0, v155
	v_rcp_f32_e32 v155, v155
	s_nop 0
	v_mul_f32_e32 v155, v133, v155
	ds_write_b32 v153, v155 offset:2048
	v_mbcnt_lo_u32_b32 v2, -1, 0
	v_mbcnt_hi_u32_b32 v2, -1, v2
	v_and_b32_e32 v4, 64, v2
	v_xor_b32_e32 v3, 32, v2
	v_add_u32_e32 v4, 64, v4
	v_cmp_lt_i32_e32 vcc, v3, v4
	v_lshrrev_b32_e32 v7, 5, v1
	s_movk_i32 s3, 0x220
	v_cndmask_b32_e32 v2, v2, v3, vcc
	v_lshlrev_b32_e32 v40, 2, v2
	v_lshl_or_b32 v2, v38, 7, v7
	v_mul_u32_u24_e32 v2, 0x1800, v2
	v_lshlrev_b32_e32 v10, 2, v2
	v_add_u32_e32 v2, 0x24000, v10
	v_mov_b32_e32 v3, 0
	v_lshl_add_u64 v[4:5], s[44:45], 0, v[2:3]
	v_add_u32_e32 v2, 0x18000, v10
	v_lshl_add_u64 v[8:9], s[44:45], 0, v[2:3]
	v_add_u32_e32 v2, 0xc000, v10
	v_lshl_add_u64 v[10:11], s[44:45], 0, v[2:3]
	v_lshlrev_b32_e32 v2, 2, v7
	v_lshl_or_b32 v2, v38, 9, v2
	s_waitcnt lgkmcnt(0)
	s_barrier
	v_cmp_gt_u32_e64 s[4:5], s3, v180
	s_load_dword s3, s[0:1], 0xb8
	v_add_u32_e32 v41, 0, v2
	v_mul_u32_u24_e32 v2, 0xc0000, v38
	v_mul_u32_u24_e32 v7, 0x1800, v7
	v_or_b32_e32 v2, v2, v7
	s_add_u32 s12, s30, 0x1a90000
	v_and_b32_e32 v39, 31, v180
	v_lshlrev_b32_e32 v2, 2, v2
	s_addc_u32 s13, s31, 0
	s_add_i32 s6, 0, 0x11000
	s_movk_i32 s7, 0x1800
	v_lshl_or_b32 v6, s2, 5, v39
	v_lshl_add_u64 v[12:13], s[44:45], 0, v[2:3]
	v_lshrrev_b32_e32 v2, 5, v180
	v_lshlrev_b32_e32 v7, 2, v39
	v_lshl_add_u32 v14, v1, 2, s6
	s_add_u32 s8, s0, 0xb8
	v_mul_u32_u24_e32 v15, 0x880, v38
	v_mad_u32_u24 v43, v2, s7, v6
	v_lshl_or_b32 v2, v2, 7, v7
	v_cmp_gt_u32_e32 vcc, 32, v1
	s_addc_u32 s9, s1, 0
	s_waitcnt lgkmcnt(0)
	s_lshl_b32 s38, s3, 5
	v_add_u32_e32 v42, 0xfffffe00, v180
	v_add_u32_e32 v44, s6, v2
	s_mov_b64 s[14:15], 0x30000
	v_add_u32_e32 v45, v14, v15
	s_mov_b32 s39, s2
	s_branch .LBB0_13
